# MoBA V stored as pre-transposed MFMA fragments (P1 epilogue transposes each 16-key group through a small LDS scratch); MoBA loops now load K and V fragments straight into MFMA operand registers, no LD
# speedup vs baseline: 1.0169x; 1.0169x over previous
; DI unsigned cvt_pk(float lo, float hi) { const f32x2 v = {lo, hi}; return __builtin_bit_cast(unsigned, __builtin_convertvector(v, bf16v2)); }
;     __device__ __forceinline__ void operator()(const f32x4 (&acc)[2][2][4][2], const Unit& u, int wr, int wc, int fr, int fq) const {
;     ...
;         } else if (mode == 1) {
; #pragma unroll
;             for (int ai = 0; ai < 2; ++ai)
; #pragma unroll
;                 for (int m = 0; m < 4; ++m) {
;                     const int s = sbase + ai * 128 + m * 16; const float r = ROW_RS(ai, m);
;                     bf16_t* rp = dst + ((bh * SEQ + s) * 64 + 8 * fq);
; #pragma unroll
;                     for (int bj = 0; bj < 2; ++bj) {
;                         const f32x4 v0 = acc[ai][bj][m][0] * r, v1 = acc[ai][bj][m][1] * r;
;                         u32x4 w; w.x = cvt_pk(v0[0], v0[1]); w.y = cvt_pk(v0[2], v0[3]); w.z = cvt_pk(v1[0], v1[1]); w.w = cvt_pk(v1[2], v1[3]);
;                         *(u32x4*)(rp + 32 * bj) = w;
;                     }
;                 }
.LBB0_419:
	s_andn2_b64 vcc, exec, s[90:91]
	s_cbranch_vccnz .LBB0_421
	s_cmp_eq_u64 s[6:7], s[64:65]
	s_cbranch_scc1 .Lvt_epi
	s_lshl_b64 s[44:45], s[82:83], 19
	s_add_u32 s44, s6, s44
	s_addc_u32 s45, s7, s45
	v_lshlrev_b32_e32 v148, 1, v150
	v_ashrrev_i32_e32 v169, 31, v168
	v_lshl_add_u64 v[136:137], s[44:45], 0, v[148:149]
	v_lshlrev_b64 v[130:131], 7, v[168:169]
	s_waitcnt vmcnt(0)
	v_pk_mul_f32 v[134:135], v[126:127], v[128:129] op_sel_hi:[1,0]
	v_pk_mul_f32 v[132:133], v[124:125], v[128:129] op_sel_hi:[1,0]
	v_pk_mul_f32 v[138:139], v[118:119], v[128:129] op_sel_hi:[1,0]
	v_pk_mul_f32 v[178:179], v[116:117], v[128:129] op_sel_hi:[1,0]
	v_lshl_add_u64 v[130:131], v[136:137], 0, v[130:131]
	v_cvt_pk_bf16_f32 v132, v132, v133
	v_cvt_pk_bf16_f32 v133, v134, v135
	v_cvt_pk_bf16_f32 v134, v178, v179
	v_cvt_pk_bf16_f32 v135, v138, v139
	global_store_dwordx4 v[130:131], v[132:135], off
	v_pk_mul_f32 v[138:139], v[114:115], v[128:129] op_sel_hi:[1,0]
	v_pk_mul_f32 v[178:179], v[112:113], v[128:129] op_sel_hi:[1,0]
	v_pk_mul_f32 v[134:135], v[122:123], v[128:129] op_sel_hi:[1,0]
	v_pk_mul_f32 v[132:133], v[120:121], v[128:129] op_sel_hi:[1,0]
	v_pk_mul_f32 v[182:183], v[100:101], v[200:201] op_sel_hi:[1,0]
	v_cvt_pk_bf16_f32 v132, v132, v133
	v_cvt_pk_bf16_f32 v133, v134, v135
	v_cvt_pk_bf16_f32 v134, v178, v179
	v_cvt_pk_bf16_f32 v135, v138, v139
	global_store_dwordx4 v[130:131], v[132:135], off offset:64
	v_pk_mul_f32 v[178:179], v[102:103], v[200:201] op_sel_hi:[1,0]
	s_movk_i32 s2, 0x4000
	v_or_b32_e32 v132, 16, v168
	v_ashrrev_i32_e32 v133, 31, v132
	v_lshlrev_b64 v[132:133], 7, v[132:133]
	v_lshl_add_u64 v[138:139], v[136:137], 0, v[132:133]
	v_pk_mul_f32 v[134:135], v[110:111], v[200:201] op_sel_hi:[1,0]
	v_pk_mul_f32 v[132:133], v[108:109], v[200:201] op_sel_hi:[1,0]
	s_mov_b64 s[44:45], 0x4000
	v_cvt_pk_bf16_f32 v132, v132, v133
	v_cvt_pk_bf16_f32 v133, v134, v135
	v_cvt_pk_bf16_f32 v134, v182, v183
	v_cvt_pk_bf16_f32 v135, v178, v179
	global_store_dwordx4 v[138:139], v[132:135], off
	v_pk_mul_f32 v[178:179], v[98:99], v[200:201] op_sel_hi:[1,0]
	v_pk_mul_f32 v[182:183], v[96:97], v[200:201] op_sel_hi:[1,0]
	v_pk_mul_f32 v[134:135], v[106:107], v[200:201] op_sel_hi:[1,0]
	v_pk_mul_f32 v[132:133], v[104:105], v[200:201] op_sel_hi:[1,0]
	v_pk_mul_f32 v[184:185], v[48:49], v[174:175] op_sel_hi:[1,0]
	v_cvt_pk_bf16_f32 v132, v132, v133
	v_cvt_pk_bf16_f32 v133, v134, v135
	v_cvt_pk_bf16_f32 v134, v182, v183
	v_cvt_pk_bf16_f32 v135, v178, v179
	global_store_dwordx4 v[138:139], v[132:135], off offset:64
	v_pk_mul_f32 v[178:179], v[86:87], v[180:181] op_sel_hi:[1,0]
	v_pk_mul_f32 v[182:183], v[84:85], v[180:181] op_sel_hi:[1,0]
	v_or_b32_e32 v132, 32, v168
	v_ashrrev_i32_e32 v133, 31, v132
	v_lshlrev_b64 v[132:133], 7, v[132:133]
	v_lshl_add_u64 v[138:139], v[136:137], 0, v[132:133]
	v_pk_mul_f32 v[134:135], v[94:95], v[180:181] op_sel_hi:[1,0]
	v_pk_mul_f32 v[132:133], v[92:93], v[180:181] op_sel_hi:[1,0]
	s_nop 0
	v_cvt_pk_bf16_f32 v132, v132, v133
	v_cvt_pk_bf16_f32 v133, v134, v135
	v_cvt_pk_bf16_f32 v134, v182, v183
	v_cvt_pk_bf16_f32 v135, v178, v179
	global_store_dwordx4 v[138:139], v[132:135], off
	v_pk_mul_f32 v[178:179], v[82:83], v[180:181] op_sel_hi:[1,0]
	v_pk_mul_f32 v[182:183], v[80:81], v[180:181] op_sel_hi:[1,0]
	v_pk_mul_f32 v[134:135], v[90:91], v[180:181] op_sel_hi:[1,0]
	v_pk_mul_f32 v[132:133], v[88:89], v[180:181] op_sel_hi:[1,0]
	s_nop 0
	v_cvt_pk_bf16_f32 v132, v132, v133
	v_cvt_pk_bf16_f32 v133, v134, v135
	v_cvt_pk_bf16_f32 v134, v182, v183
	v_cvt_pk_bf16_f32 v135, v178, v179
	global_store_dwordx4 v[138:139], v[132:135], off offset:64
	v_pk_mul_f32 v[138:139], v[70:71], v[176:177] op_sel_hi:[1,0]
	v_pk_mul_f32 v[178:179], v[68:69], v[176:177] op_sel_hi:[1,0]
	v_or_b32_e32 v132, 48, v168
	v_ashrrev_i32_e32 v133, 31, v132
	v_lshlrev_b64 v[132:133], 7, v[132:133]
	v_lshl_add_u64 v[136:137], v[136:137], 0, v[132:133]
	v_pk_mul_f32 v[134:135], v[78:79], v[176:177] op_sel_hi:[1,0]
	v_pk_mul_f32 v[132:133], v[76:77], v[176:177] op_sel_hi:[1,0]
	v_pk_mul_f32 v[182:183], v[50:51], v[174:175] op_sel_hi:[1,0]
	v_cvt_pk_bf16_f32 v132, v132, v133
	v_cvt_pk_bf16_f32 v133, v134, v135
	v_cvt_pk_bf16_f32 v134, v178, v179
	v_cvt_pk_bf16_f32 v135, v138, v139
	global_store_dwordx4 v[136:137], v[132:135], off
	v_pk_mul_f32 v[138:139], v[66:67], v[176:177] op_sel_hi:[1,0]
	v_pk_mul_f32 v[178:179], v[64:65], v[176:177] op_sel_hi:[1,0]
	v_pk_mul_f32 v[134:135], v[74:75], v[176:177] op_sel_hi:[1,0]
	v_pk_mul_f32 v[132:133], v[72:73], v[176:177] op_sel_hi:[1,0]
	s_nop 0
	v_cvt_pk_bf16_f32 v132, v132, v133
	v_cvt_pk_bf16_f32 v133, v134, v135
	v_cvt_pk_bf16_f32 v134, v178, v179
	v_cvt_pk_bf16_f32 v135, v138, v139
	global_store_dwordx4 v[136:137], v[132:135], off offset:64
	v_pk_mul_f32 v[138:139], v[54:55], v[174:175] op_sel_hi:[1,0]
	v_pk_mul_f32 v[178:179], v[52:53], v[174:175] op_sel_hi:[1,0]
	v_pk_mul_f32 v[134:135], v[62:63], v[174:175] op_sel_hi:[1,0]
	v_pk_mul_f32 v[132:133], v[60:61], v[174:175] op_sel_hi:[1,0]
	v_lshl_add_u64 v[136:137], v[130:131], 0, s[44:45]
	v_cvt_pk_bf16_f32 v132, v132, v133
	v_cvt_pk_bf16_f32 v133, v134, v135
	v_cvt_pk_bf16_f32 v135, v138, v139
	v_add_co_u32_e32 v138, vcc, s2, v130
	s_movk_i32 s2, 0x5000
	s_nop 0
	v_addc_co_u32_e32 v139, vcc, 0, v131, vcc
	v_cvt_pk_bf16_f32 v134, v178, v179
	v_add_co_u32_e32 v178, vcc, s2, v130
	s_mov_b64 s[44:45], 0x4800
	s_nop 0
	v_addc_co_u32_e32 v179, vcc, 0, v131, vcc
	global_store_dwordx4 v[178:179], v[132:135], off offset:-4096
	s_nop 1
	v_pk_mul_f32 v[134:135], v[58:59], v[174:175] op_sel_hi:[1,0]
	v_pk_mul_f32 v[132:133], v[56:57], v[174:175] op_sel_hi:[1,0]
; #define LAS __attribute__((address_space(3)))
; DI unsigned cvt_pk(float lo, float hi) { const f32x2 v = {lo, hi}; return __builtin_bit_cast(unsigned, __builtin_convertvector(v, bf16v2)); }
;     __device__ __forceinline__ void operator()(const f32x4 (&acc)[2][2][4][2], const Unit& u, int wr, int wc, int fr, int fq) const {
;     ...
;         } else if (mode == 1) {
; #pragma unroll
;             for (int ai = 0; ai < 2; ++ai)
; #pragma unroll
;                 for (int m = 0; m < 4; ++m) {
;                     const int s = sbase + ai * 128 + m * 16; const float r = ROW_RS(ai, m);
;                     bf16_t* rp = dst + ((bh * SEQ + s) * 64 + 8 * fq);
; #pragma unroll
;                     for (int bj = 0; bj < 2; ++bj) {
;                         const f32x4 v0 = acc[ai][bj][m][0] * r, v1 = acc[ai][bj][m][1] * r;
;                         u32x4 w; w.x = cvt_pk(v0[0], v0[1]); w.y = cvt_pk(v0[2], v0[3]); w.z = cvt_pk(v1[0], v1[1]); w.w = cvt_pk(v1[2], v1[3]);
;                         *(u32x4*)(rp + 32 * bj) = w;
;                     }
;                 }
; DI void load_vfrag(bf16x8 (&vf)[2][2], LAS unsigned char* buf, int lane) {
;     const int h = lane >> 5, q = (lane & 15) >> 2, p = lane & 3, blk = (lane >> 4) & 1;
;     LAS unsigned char* vb = buf + 32 * TROW + (4 * h + q) * TROW + 32 * blk + 8 * p;
; #pragma unroll
;     for (int dt = 0; dt < 2; ++dt)
; #pragma unroll
;         for (int s2 = 0; s2 < 2; ++s2) {
;             const s16x4 lo = __builtin_amdgcn_ds_read_tr16_b64_v4i16((LAS s16x4*)(vb + (16 * s2) * TROW + 64 * dt));
;             const s16x4 hi4 = __builtin_amdgcn_ds_read_tr16_b64_v4i16((LAS s16x4*)(vb + (16 * s2 + 8) * TROW + 64 * dt));
;             vf[dt][s2] = __builtin_shufflevector(lo, hi4, 0, 1, 2, 3, 4, 5, 6, 7);
;         }
	s_nop 0
	v_cvt_pk_bf16_f32 v132, v132, v133
	v_cvt_pk_bf16_f32 v133, v134, v135
	v_cvt_pk_bf16_f32 v134, v184, v185
	v_cvt_pk_bf16_f32 v135, v182, v183
	global_store_dwordx4 v[136:137], v[132:135], off offset:64
	v_pk_mul_f32 v[182:183], v[38:39], v[172:173] op_sel_hi:[1,0]
	v_pk_mul_f32 v[184:185], v[36:37], v[172:173] op_sel_hi:[1,0]
	v_pk_mul_f32 v[134:135], v[46:47], v[172:173] op_sel_hi:[1,0]
	v_pk_mul_f32 v[132:133], v[44:45], v[172:173] op_sel_hi:[1,0]
	v_lshl_add_u64 v[136:137], v[130:131], 0, s[44:45]
	v_cvt_pk_bf16_f32 v132, v132, v133
	v_cvt_pk_bf16_f32 v133, v134, v135
	v_cvt_pk_bf16_f32 v134, v184, v185
	v_cvt_pk_bf16_f32 v135, v182, v183
	global_store_dwordx4 v[138:139], v[132:135], off offset:2048
	v_pk_mul_f32 v[138:139], v[34:35], v[172:173] op_sel_hi:[1,0]
	v_pk_mul_f32 v[182:183], v[32:33], v[172:173] op_sel_hi:[1,0]
	v_pk_mul_f32 v[134:135], v[42:43], v[172:173] op_sel_hi:[1,0]
	v_pk_mul_f32 v[132:133], v[40:41], v[172:173] op_sel_hi:[1,0]
	s_mov_b64 s[44:45], 0x5000
	v_cvt_pk_bf16_f32 v132, v132, v133
	v_cvt_pk_bf16_f32 v133, v134, v135
	v_cvt_pk_bf16_f32 v134, v182, v183
	v_cvt_pk_bf16_f32 v135, v138, v139
	global_store_dwordx4 v[136:137], v[132:135], off offset:64
	v_pk_mul_f32 v[138:139], v[22:23], v[170:171] op_sel_hi:[1,0]
	v_pk_mul_f32 v[182:183], v[20:21], v[170:171] op_sel_hi:[1,0]
	v_pk_mul_f32 v[134:135], v[30:31], v[170:171] op_sel_hi:[1,0]
	v_pk_mul_f32 v[132:133], v[28:29], v[170:171] op_sel_hi:[1,0]
	v_lshl_add_u64 v[136:137], v[130:131], 0, s[44:45]
	v_cvt_pk_bf16_f32 v132, v132, v133
	v_cvt_pk_bf16_f32 v133, v134, v135
	v_cvt_pk_bf16_f32 v134, v182, v183
	v_cvt_pk_bf16_f32 v135, v138, v139
	global_store_dwordx4 v[178:179], v[132:135], off
	v_pk_mul_f32 v[138:139], v[18:19], v[170:171] op_sel_hi:[1,0]
	v_pk_mul_f32 v[182:183], v[16:17], v[170:171] op_sel_hi:[1,0]
	v_pk_mul_f32 v[134:135], v[26:27], v[170:171] op_sel_hi:[1,0]
	v_pk_mul_f32 v[132:133], v[24:25], v[170:171] op_sel_hi:[1,0]
	s_mov_b64 s[44:45], 0x5800
	v_cvt_pk_bf16_f32 v132, v132, v133
	v_cvt_pk_bf16_f32 v133, v134, v135
	v_cvt_pk_bf16_f32 v134, v182, v183
	v_cvt_pk_bf16_f32 v135, v138, v139
	global_store_dwordx4 v[136:137], v[132:135], off offset:64
	v_pk_mul_f32 v[136:137], v[6:7], v[166:167] op_sel_hi:[1,0]
	v_pk_mul_f32 v[138:139], v[4:5], v[166:167] op_sel_hi:[1,0]
	v_lshl_add_u64 v[134:135], v[130:131], 0, s[44:45]
	v_pk_mul_f32 v[132:133], v[14:15], v[166:167] op_sel_hi:[1,0]
	v_pk_mul_f32 v[130:131], v[12:13], v[166:167] op_sel_hi:[1,0]
	s_nop 0
	v_cvt_pk_bf16_f32 v130, v130, v131
	v_cvt_pk_bf16_f32 v131, v132, v133
	v_cvt_pk_bf16_f32 v132, v138, v139
	v_cvt_pk_bf16_f32 v133, v136, v137
	global_store_dwordx4 v[178:179], v[130:133], off offset:2048
	v_pk_mul_f32 v[136:137], v[2:3], v[166:167] op_sel_hi:[1,0]
	v_pk_mul_f32 v[138:139], v[0:1], v[166:167] op_sel_hi:[1,0]
	v_pk_mul_f32 v[132:133], v[10:11], v[166:167] op_sel_hi:[1,0]
	v_pk_mul_f32 v[130:131], v[8:9], v[166:167] op_sel_hi:[1,0]
	s_nop 0
	v_cvt_pk_bf16_f32 v130, v130, v131
	v_cvt_pk_bf16_f32 v131, v132, v133
	v_cvt_pk_bf16_f32 v132, v138, v139
	v_cvt_pk_bf16_f32 v133, v136, v137
	global_store_dwordx4 v[134:135], v[130:133], off offset:64
	s_branch .LBB0_421
.Lvt_epi:
	s_cmp_lg_u64 s[14:15], 0
	s_cselect_b32 s2, 4, 0
	s_add_i32 s2, s2, s97
	s_mul_i32 s2, s2, 0x900
	s_add_i32 s2, s2, 0x20000
	v_and_b32_e32 v182, 15, v181
	v_lshrrev_b32_e32 v183, 4, v181
	v_mul_u32_u24_e32 v182, 0x90, v182
	v_lshl_add_u32 v182, v183, 4, v182
	v_add_u32_e32 v182, s2, v182
	v_lshrrev_b32_e32 v183, 5, v181
	v_bfe_u32 v184, v181, 2, 2
	v_lshl_add_u32 v183, v183, 2, v184
	v_mul_u32_u24_e32 v183, 0x90, v183
	v_bfe_u32 v184, v181, 4, 1
	v_lshl_add_u32 v183, v184, 5, v183
	v_and_b32_e32 v184, 3, v181
	v_lshl_add_u32 v183, v184, 3, v183
	v_add_u32_e32 v183, s2, v183
	s_lshl_b64 s[44:45], s[82:83], 19
	s_add_u32 s44, s6, s44
	s_addc_u32 s45, s7, s45
	v_and_b32_e32 v184, 0xffffffe0, v168
	v_lshlrev_b32_e32 v184, 7, v184
	v_lshl_add_u32 v184, v181, 4, v184
	s_waitcnt vmcnt(0)
	v_pk_mul_f32 v[186:187], v[124:125], v[128:129] op_sel_hi:[1,0]
	v_pk_mul_f32 v[188:189], v[126:127], v[128:129] op_sel_hi:[1,0]
	v_pk_mul_f32 v[190:191], v[116:117], v[128:129] op_sel_hi:[1,0]
	v_pk_mul_f32 v[192:193], v[118:119], v[128:129] op_sel_hi:[1,0]
	v_cvt_pk_bf16_f32 v194, v186, v187
	v_cvt_pk_bf16_f32 v195, v188, v189
	v_cvt_pk_bf16_f32 v196, v190, v191
	v_cvt_pk_bf16_f32 v197, v192, v193
	ds_write_b128 v182, v[194:197]
	v_pk_mul_f32 v[186:187], v[120:121], v[128:129] op_sel_hi:[1,0]
	v_pk_mul_f32 v[188:189], v[122:123], v[128:129] op_sel_hi:[1,0]
	v_pk_mul_f32 v[190:191], v[112:113], v[128:129] op_sel_hi:[1,0]
	v_pk_mul_f32 v[192:193], v[114:115], v[128:129] op_sel_hi:[1,0]
	v_cvt_pk_bf16_f32 v202, v186, v187
	v_cvt_pk_bf16_f32 v203, v188, v189
	v_cvt_pk_bf16_f32 v204, v190, v191
	v_cvt_pk_bf16_f32 v205, v192, v193
	ds_write_b128 v182, v[202:205] offset:64
	ds_read_b64_tr_b16 v[206:207], v183
	ds_read_b64_tr_b16 v[208:209], v183 offset:1152
	ds_read_b64_tr_b16 v[210:211], v183 offset:64
	ds_read_b64_tr_b16 v[212:213], v183 offset:1216
	s_waitcnt lgkmcnt(0)
; #define LAS __attribute__((address_space(3)))
; DI unsigned cvt_pk(float lo, float hi) { const f32x2 v = {lo, hi}; return __builtin_bit_cast(unsigned, __builtin_convertvector(v, bf16v2)); }
;     __device__ __forceinline__ void operator()(const f32x4 (&acc)[2][2][4][2], const Unit& u, int wr, int wc, int fr, int fq) const {
;     ...
;         } else if (mode == 1) {
; #pragma unroll
;             for (int ai = 0; ai < 2; ++ai)
; #pragma unroll
;                 for (int m = 0; m < 4; ++m) {
;                     const int s = sbase + ai * 128 + m * 16; const float r = ROW_RS(ai, m);
;                     bf16_t* rp = dst + ((bh * SEQ + s) * 64 + 8 * fq);
; #pragma unroll
;                     for (int bj = 0; bj < 2; ++bj) {
;                         const f32x4 v0 = acc[ai][bj][m][0] * r, v1 = acc[ai][bj][m][1] * r;
;                         u32x4 w; w.x = cvt_pk(v0[0], v0[1]); w.y = cvt_pk(v0[2], v0[3]); w.z = cvt_pk(v1[0], v1[1]); w.w = cvt_pk(v1[2], v1[3]);
;                         *(u32x4*)(rp + 32 * bj) = w;
;                     }
;                 }
; DI void load_vfrag(bf16x8 (&vf)[2][2], LAS unsigned char* buf, int lane) {
;     const int h = lane >> 5, q = (lane & 15) >> 2, p = lane & 3, blk = (lane >> 4) & 1;
;     LAS unsigned char* vb = buf + 32 * TROW + (4 * h + q) * TROW + 32 * blk + 8 * p;
; #pragma unroll
;     for (int dt = 0; dt < 2; ++dt)
; #pragma unroll
;         for (int s2 = 0; s2 < 2; ++s2) {
;             const s16x4 lo = __builtin_amdgcn_ds_read_tr16_b64_v4i16((LAS s16x4*)(vb + (16 * s2) * TROW + 64 * dt));
;             const s16x4 hi4 = __builtin_amdgcn_ds_read_tr16_b64_v4i16((LAS s16x4*)(vb + (16 * s2 + 8) * TROW + 64 * dt));
;             vf[dt][s2] = __builtin_shufflevector(lo, hi4, 0, 1, 2, 3, 4, 5, 6, 7);
;         }
	global_store_dwordx4 v184, v[206:209], s[44:45]
	global_store_dwordx4 v184, v[210:213], s[44:45] offset:2048
	v_pk_mul_f32 v[186:187], v[108:109], v[200:201] op_sel_hi:[1,0]
	v_pk_mul_f32 v[188:189], v[110:111], v[200:201] op_sel_hi:[1,0]
	v_pk_mul_f32 v[190:191], v[100:101], v[200:201] op_sel_hi:[1,0]
	v_pk_mul_f32 v[192:193], v[102:103], v[200:201] op_sel_hi:[1,0]
	v_cvt_pk_bf16_f32 v194, v186, v187
	v_cvt_pk_bf16_f32 v195, v188, v189
	v_cvt_pk_bf16_f32 v196, v190, v191
	v_cvt_pk_bf16_f32 v197, v192, v193
	ds_write_b128 v182, v[194:197]
	v_pk_mul_f32 v[186:187], v[104:105], v[200:201] op_sel_hi:[1,0]
	v_pk_mul_f32 v[188:189], v[106:107], v[200:201] op_sel_hi:[1,0]
	v_pk_mul_f32 v[190:191], v[96:97], v[200:201] op_sel_hi:[1,0]
	v_pk_mul_f32 v[192:193], v[98:99], v[200:201] op_sel_hi:[1,0]
	v_cvt_pk_bf16_f32 v202, v186, v187
	v_cvt_pk_bf16_f32 v203, v188, v189
	v_cvt_pk_bf16_f32 v204, v190, v191
	v_cvt_pk_bf16_f32 v205, v192, v193
	ds_write_b128 v182, v[202:205] offset:64
	ds_read_b64_tr_b16 v[206:207], v183
	ds_read_b64_tr_b16 v[208:209], v183 offset:1152
	ds_read_b64_tr_b16 v[210:211], v183 offset:64
	ds_read_b64_tr_b16 v[212:213], v183 offset:1216
	s_waitcnt lgkmcnt(0)
	global_store_dwordx4 v184, v[206:209], s[44:45] offset:1024
	global_store_dwordx4 v184, v[210:213], s[44:45] offset:3072
	v_pk_mul_f32 v[186:187], v[92:93], v[180:181] op_sel_hi:[1,0]
	v_pk_mul_f32 v[188:189], v[94:95], v[180:181] op_sel_hi:[1,0]
	v_pk_mul_f32 v[190:191], v[84:85], v[180:181] op_sel_hi:[1,0]
	v_pk_mul_f32 v[192:193], v[86:87], v[180:181] op_sel_hi:[1,0]
	v_cvt_pk_bf16_f32 v194, v186, v187
	v_cvt_pk_bf16_f32 v195, v188, v189
	v_cvt_pk_bf16_f32 v196, v190, v191
	v_cvt_pk_bf16_f32 v197, v192, v193
	ds_write_b128 v182, v[194:197]
	v_pk_mul_f32 v[186:187], v[88:89], v[180:181] op_sel_hi:[1,0]
	v_pk_mul_f32 v[188:189], v[90:91], v[180:181] op_sel_hi:[1,0]
	v_pk_mul_f32 v[190:191], v[80:81], v[180:181] op_sel_hi:[1,0]
	v_pk_mul_f32 v[192:193], v[82:83], v[180:181] op_sel_hi:[1,0]
	v_cvt_pk_bf16_f32 v202, v186, v187
	v_cvt_pk_bf16_f32 v203, v188, v189
	v_cvt_pk_bf16_f32 v204, v190, v191
	v_cvt_pk_bf16_f32 v205, v192, v193
	ds_write_b128 v182, v[202:205] offset:64
	ds_read_b64_tr_b16 v[206:207], v183
	ds_read_b64_tr_b16 v[208:209], v183 offset:1152
	ds_read_b64_tr_b16 v[210:211], v183 offset:64
	ds_read_b64_tr_b16 v[212:213], v183 offset:1216
	v_add_u32_e32 v185, 0x1000, v184
	s_waitcnt lgkmcnt(0)
	global_store_dwordx4 v185, v[206:209], s[44:45]
	global_store_dwordx4 v185, v[210:213], s[44:45] offset:2048
	v_pk_mul_f32 v[186:187], v[76:77], v[176:177] op_sel_hi:[1,0]
	v_pk_mul_f32 v[188:189], v[78:79], v[176:177] op_sel_hi:[1,0]
	v_pk_mul_f32 v[190:191], v[68:69], v[176:177] op_sel_hi:[1,0]
	v_pk_mul_f32 v[192:193], v[70:71], v[176:177] op_sel_hi:[1,0]
	v_cvt_pk_bf16_f32 v194, v186, v187
	v_cvt_pk_bf16_f32 v195, v188, v189
	v_cvt_pk_bf16_f32 v196, v190, v191
	v_cvt_pk_bf16_f32 v197, v192, v193
	ds_write_b128 v182, v[194:197]
	v_pk_mul_f32 v[186:187], v[72:73], v[176:177] op_sel_hi:[1,0]
	v_pk_mul_f32 v[188:189], v[74:75], v[176:177] op_sel_hi:[1,0]
	v_pk_mul_f32 v[190:191], v[64:65], v[176:177] op_sel_hi:[1,0]
	v_pk_mul_f32 v[192:193], v[66:67], v[176:177] op_sel_hi:[1,0]
	v_cvt_pk_bf16_f32 v202, v186, v187
	v_cvt_pk_bf16_f32 v203, v188, v189
	v_cvt_pk_bf16_f32 v204, v190, v191
	v_cvt_pk_bf16_f32 v205, v192, v193
	ds_write_b128 v182, v[202:205] offset:64
	ds_read_b64_tr_b16 v[206:207], v183
	ds_read_b64_tr_b16 v[208:209], v183 offset:1152
	ds_read_b64_tr_b16 v[210:211], v183 offset:64
	ds_read_b64_tr_b16 v[212:213], v183 offset:1216
	v_add_u32_e32 v185, 0x1000, v184
	s_waitcnt lgkmcnt(0)
	global_store_dwordx4 v185, v[206:209], s[44:45] offset:1024
	global_store_dwordx4 v185, v[210:213], s[44:45] offset:3072
	v_pk_mul_f32 v[186:187], v[60:61], v[174:175] op_sel_hi:[1,0]
	v_pk_mul_f32 v[188:189], v[62:63], v[174:175] op_sel_hi:[1,0]
	v_pk_mul_f32 v[190:191], v[52:53], v[174:175] op_sel_hi:[1,0]
	v_pk_mul_f32 v[192:193], v[54:55], v[174:175] op_sel_hi:[1,0]
	v_cvt_pk_bf16_f32 v194, v186, v187
	v_cvt_pk_bf16_f32 v195, v188, v189
	v_cvt_pk_bf16_f32 v196, v190, v191
	v_cvt_pk_bf16_f32 v197, v192, v193
	ds_write_b128 v182, v[194:197]
	v_pk_mul_f32 v[186:187], v[56:57], v[174:175] op_sel_hi:[1,0]
	v_pk_mul_f32 v[188:189], v[58:59], v[174:175] op_sel_hi:[1,0]
	v_pk_mul_f32 v[190:191], v[48:49], v[174:175] op_sel_hi:[1,0]
	v_pk_mul_f32 v[192:193], v[50:51], v[174:175] op_sel_hi:[1,0]
	v_cvt_pk_bf16_f32 v202, v186, v187
	v_cvt_pk_bf16_f32 v203, v188, v189
	v_cvt_pk_bf16_f32 v204, v190, v191
	v_cvt_pk_bf16_f32 v205, v192, v193
	ds_write_b128 v182, v[202:205] offset:64
	ds_read_b64_tr_b16 v[206:207], v183
	ds_read_b64_tr_b16 v[208:209], v183 offset:1152
	ds_read_b64_tr_b16 v[210:211], v183 offset:64
	ds_read_b64_tr_b16 v[212:213], v183 offset:1216
	v_add_u32_e32 v185, 0x4000, v184
	s_waitcnt lgkmcnt(0)
; DI unsigned cvt_pk(float lo, float hi) { const f32x2 v = {lo, hi}; return __builtin_bit_cast(unsigned, __builtin_convertvector(v, bf16v2)); }
;     __device__ __forceinline__ void operator()(const f32x4 (&acc)[2][2][4][2], const Unit& u, int wr, int wc, int fr, int fq) const {
;     ...
;         } else if (mode == 1) {
; #pragma unroll
;             for (int ai = 0; ai < 2; ++ai)
; #pragma unroll
;                 for (int m = 0; m < 4; ++m) {
;                     const int s = sbase + ai * 128 + m * 16; const float r = ROW_RS(ai, m);
;                     bf16_t* rp = dst + ((bh * SEQ + s) * 64 + 8 * fq);
; #pragma unroll
;                     for (int bj = 0; bj < 2; ++bj) {
;                         const f32x4 v0 = acc[ai][bj][m][0] * r, v1 = acc[ai][bj][m][1] * r;
;                         u32x4 w; w.x = cvt_pk(v0[0], v0[1]); w.y = cvt_pk(v0[2], v0[3]); w.z = cvt_pk(v1[0], v1[1]); w.w = cvt_pk(v1[2], v1[3]);
;                         *(u32x4*)(rp + 32 * bj) = w;
;                     }
;                 }
	global_store_dwordx4 v185, v[206:209], s[44:45]
	global_store_dwordx4 v185, v[210:213], s[44:45] offset:2048
	v_pk_mul_f32 v[186:187], v[44:45], v[172:173] op_sel_hi:[1,0]
	v_pk_mul_f32 v[188:189], v[46:47], v[172:173] op_sel_hi:[1,0]
	v_pk_mul_f32 v[190:191], v[36:37], v[172:173] op_sel_hi:[1,0]
	v_pk_mul_f32 v[192:193], v[38:39], v[172:173] op_sel_hi:[1,0]
	v_cvt_pk_bf16_f32 v194, v186, v187
	v_cvt_pk_bf16_f32 v195, v188, v189
	v_cvt_pk_bf16_f32 v196, v190, v191
	v_cvt_pk_bf16_f32 v197, v192, v193
	ds_write_b128 v182, v[194:197]
	v_pk_mul_f32 v[186:187], v[40:41], v[172:173] op_sel_hi:[1,0]
	v_pk_mul_f32 v[188:189], v[42:43], v[172:173] op_sel_hi:[1,0]
	v_pk_mul_f32 v[190:191], v[32:33], v[172:173] op_sel_hi:[1,0]
	v_pk_mul_f32 v[192:193], v[34:35], v[172:173] op_sel_hi:[1,0]
	v_cvt_pk_bf16_f32 v202, v186, v187
	v_cvt_pk_bf16_f32 v203, v188, v189
	v_cvt_pk_bf16_f32 v204, v190, v191
	v_cvt_pk_bf16_f32 v205, v192, v193
	ds_write_b128 v182, v[202:205] offset:64
	ds_read_b64_tr_b16 v[206:207], v183
	ds_read_b64_tr_b16 v[208:209], v183 offset:1152
	ds_read_b64_tr_b16 v[210:211], v183 offset:64
	ds_read_b64_tr_b16 v[212:213], v183 offset:1216
	v_add_u32_e32 v185, 0x4000, v184
	s_waitcnt lgkmcnt(0)
	global_store_dwordx4 v185, v[206:209], s[44:45] offset:1024
	global_store_dwordx4 v185, v[210:213], s[44:45] offset:3072
	v_pk_mul_f32 v[186:187], v[28:29], v[170:171] op_sel_hi:[1,0]
	v_pk_mul_f32 v[188:189], v[30:31], v[170:171] op_sel_hi:[1,0]
	v_pk_mul_f32 v[190:191], v[20:21], v[170:171] op_sel_hi:[1,0]
	v_pk_mul_f32 v[192:193], v[22:23], v[170:171] op_sel_hi:[1,0]
	v_cvt_pk_bf16_f32 v194, v186, v187
	v_cvt_pk_bf16_f32 v195, v188, v189
	v_cvt_pk_bf16_f32 v196, v190, v191
	v_cvt_pk_bf16_f32 v197, v192, v193
	ds_write_b128 v182, v[194:197]
	v_pk_mul_f32 v[186:187], v[24:25], v[170:171] op_sel_hi:[1,0]
	v_pk_mul_f32 v[188:189], v[26:27], v[170:171] op_sel_hi:[1,0]
	v_pk_mul_f32 v[190:191], v[16:17], v[170:171] op_sel_hi:[1,0]
	v_pk_mul_f32 v[192:193], v[18:19], v[170:171] op_sel_hi:[1,0]
	v_cvt_pk_bf16_f32 v202, v186, v187
	v_cvt_pk_bf16_f32 v203, v188, v189
	v_cvt_pk_bf16_f32 v204, v190, v191
	v_cvt_pk_bf16_f32 v205, v192, v193
	ds_write_b128 v182, v[202:205] offset:64
	ds_read_b64_tr_b16 v[206:207], v183
	ds_read_b64_tr_b16 v[208:209], v183 offset:1152
	ds_read_b64_tr_b16 v[210:211], v183 offset:64
	ds_read_b64_tr_b16 v[212:213], v183 offset:1216
	v_add_u32_e32 v185, 0x5000, v184
	s_waitcnt lgkmcnt(0)
	global_store_dwordx4 v185, v[206:209], s[44:45]
	global_store_dwordx4 v185, v[210:213], s[44:45] offset:2048
	v_pk_mul_f32 v[186:187], v[12:13], v[166:167] op_sel_hi:[1,0]
	v_pk_mul_f32 v[188:189], v[14:15], v[166:167] op_sel_hi:[1,0]
	v_pk_mul_f32 v[190:191], v[4:5], v[166:167] op_sel_hi:[1,0]
	v_pk_mul_f32 v[192:193], v[6:7], v[166:167] op_sel_hi:[1,0]
	v_cvt_pk_bf16_f32 v194, v186, v187
	v_cvt_pk_bf16_f32 v195, v188, v189
	v_cvt_pk_bf16_f32 v196, v190, v191
	v_cvt_pk_bf16_f32 v197, v192, v193
	ds_write_b128 v182, v[194:197]
	v_pk_mul_f32 v[186:187], v[8:9], v[166:167] op_sel_hi:[1,0]
	v_pk_mul_f32 v[188:189], v[10:11], v[166:167] op_sel_hi:[1,0]
	v_pk_mul_f32 v[190:191], v[0:1], v[166:167] op_sel_hi:[1,0]
	v_pk_mul_f32 v[192:193], v[2:3], v[166:167] op_sel_hi:[1,0]
	v_cvt_pk_bf16_f32 v202, v186, v187
	v_cvt_pk_bf16_f32 v203, v188, v189
	v_cvt_pk_bf16_f32 v204, v190, v191
	v_cvt_pk_bf16_f32 v205, v192, v193
	ds_write_b128 v182, v[202:205] offset:64
	ds_read_b64_tr_b16 v[206:207], v183
	ds_read_b64_tr_b16 v[208:209], v183 offset:1152
	ds_read_b64_tr_b16 v[210:211], v183 offset:64
	ds_read_b64_tr_b16 v[212:213], v183 offset:1216
	v_add_u32_e32 v185, 0x5000, v184
	s_waitcnt lgkmcnt(0)
	global_store_dwordx4 v185, v[206:209], s[44:45] offset:1024
	global_store_dwordx4 v185, v[210:213], s[44:45] offset:3072

; #define MFMA32(a, b, c) __builtin_amdgcn_mfma_f32_32x32x16_bf16((a), (b), (c), 0, 0, 0)
; DI void core2(QT& a, QT& b, LAS unsigned char* buf, int dist0a, int dist0b, int kstride, int hi, bool elem, bool oka, bool okb, float m0, int lane) {
;     ...
;     softmax_p<false>(a.st, sa, dist0a, kstride, hi, oka, elem, 0.f);
;     {
;         bf16x8 pa[2]; pack_p(pa, sa, oka);
; #pragma unroll
;         for (int s2 = 0; s2 < 2; ++s2) {
;             const bf16x8 v0 = load_vfrag1(vb, 0, s2), v1 = load_vfrag1(vb, 1, s2);
;             a.st.o0 = MFMA32(v0, pa[s2], a.st.o0); a.st.o1 = MFMA32(v1, pa[s2], a.st.o1);
;         }
;     }
;     softmax_p<false>(b.st, sb, dist0b, kstride, hi, okb, elem, 0.f);
;     {
;         bf16x8 pb[2]; pack_p(pb, sb, okb);
; #pragma unroll
;         for (int s2 = 0; s2 < 2; ++s2) {
;             const bf16x8 v0 = load_vfrag1(vb, 0, s2), v1 = load_vfrag1(vb, 1, s2);
;             b.st.o0 = MFMA32(v0, pb[s2], b.st.o0); b.st.o1 = MFMA32(v1, pb[s2], b.st.o1);
;         }
;     }
; DI void attn_b_item(unsigned char* ws, LAS unsigned char* buf, LAS unsigned char* qbuf, LAS unsigned* tbl, LAS float* km  , int bh, int qblk, int w4, int lane) {
;     ...
;                 core2(a, b, buf, qpa - kb - 4 * h, qpb - kb - 4 * h, 1, 0x7fffffff, own && (Tc >= 2 * w4), oka, okb, m0, lane);
;             }
;             if (!okl) break;
;             nc = nl; Tc = Tl;
.LBB0_567:
	s_cmp_le_i32 s21, s86
	s_cselect_b64 s[90:91], -1, 0
	v_cndmask_b32_e64 v113, 0, 1, s[90:91]
	s_lshl_b32 s90, 1, s20
	v_and_b32_e32 v114, s90, v248
	v_cmp_ne_u32_e32 vcc, 0, v114
	s_nop 3
	v_exp_f32_e32 v98, v98
	v_exp_f32_e32 v99, v99
	v_cndmask_b32_e64 v114, 0, 1, vcc
	v_exp_f32_e32 v100, v100
	v_exp_f32_e32 v101, v101
	v_cndmask_b32_e64 v113, v114, v113, s[16:17]
	v_exp_f32_e32 v96, v96
	v_exp_f32_e32 v97, v97
	v_exp_f32_e32 v102, v102
	v_exp_f32_e32 v103, v103
	v_and_b32_e32 v113, 1, v113
	v_cmp_eq_u32_e64 s[20:21], 1, v113
	v_cvt_pk_bf16_f32 v113, v98, v99
	v_cvt_pk_bf16_f32 v114, v96, v97
	v_cndmask_b32_e64 v191, 0, v113, s[20:21]
	v_cvt_pk_bf16_f32 v113, v100, v101
	v_cndmask_b32_e64 v192, 0, v113, s[20:21]
	v_cvt_pk_bf16_f32 v113, v102, v103
	v_exp_f32_e32 v104, v104
	v_exp_f32_e32 v105, v105
	v_cndmask_b32_e64 v190, 0, v114, s[20:21]
	v_cndmask_b32_e64 v193, 0, v113, s[20:21]
	v_exp_f32_e32 v106, v106
	v_exp_f32_e32 v107, v107
	s_waitcnt vmcnt(7)
	v_mfma_f32_32x32x16_bf16 v[48:63], v[152:155], v[190:193], v[48:63]
	v_exp_f32_e32 v108, v108
	v_exp_f32_e32 v109, v109
	v_exp_f32_e32 v110, v110
	v_exp_f32_e32 v111, v111
	v_cvt_pk_bf16_f32 v113, v104, v105
	v_cndmask_b32_e64 v194, 0, v113, s[20:21]
	s_waitcnt vmcnt(5)
	v_mfma_f32_32x32x16_bf16 v[32:47], v[168:171], v[190:193], v[32:47]
	v_cvt_pk_bf16_f32 v113, v106, v107
	v_cndmask_b32_e64 v195, 0, v113, s[20:21]
	v_cvt_pk_bf16_f32 v113, v108, v109
	v_cndmask_b32_e64 v196, 0, v113, s[20:21]
	v_cvt_pk_bf16_f32 v113, v110, v111
	v_cndmask_b32_e64 v197, 0, v113, s[20:21]
	s_and_b64 vcc, exec, s[18:19]
	s_nop 0
	v_mfma_f32_32x32x16_bf16 v[48:63], v[160:163], v[194:197], v[48:63]
	s_waitcnt vmcnt(4)
	v_mfma_f32_32x32x16_bf16 v[32:47], v[176:179], v[194:197], v[32:47]
	s_cbranch_vccnz .LBB0_569
	v_sub_u32_e32 v112, v188, v112
	s_nop 0
	v_cmp_lt_i32_e32 vcc, -1, v112
	v_add_u32_e32 v113, -3, v112
	s_nop 0
	v_cndmask_b32_e32 v80, v245, v80, vcc
	v_cmp_lt_i32_e32 vcc, 0, v112
	s_nop 1
	v_cndmask_b32_e32 v81, v245, v81, vcc
	v_cmp_lt_i32_e32 vcc, 1, v112
	s_nop 1
	v_cndmask_b32_e32 v82, v245, v82, vcc
	v_cmp_lt_i32_e32 vcc, -1, v113
	v_add_u32_e32 v113, -9, v112
	s_nop 0
	v_cndmask_b32_e32 v83, v245, v83, vcc
	v_cmp_lt_i32_e32 vcc, 7, v112
	s_nop 1
	v_cndmask_b32_e32 v84, v245, v84, vcc
	v_cmp_lt_i32_e32 vcc, -1, v113
	v_add_u32_e32 v113, -10, v112
	s_nop 0
	v_cndmask_b32_e32 v85, v245, v85, vcc
	v_cmp_lt_i32_e32 vcc, -1, v113
	v_add_u32_e32 v113, -11, v112
	s_nop 0
	v_cndmask_b32_e32 v86, v245, v86, vcc
	v_cmp_lt_i32_e32 vcc, -1, v113
	v_subrev_u32_e32 v113, 17, v112
	s_nop 0
	v_cndmask_b32_e32 v87, v245, v87, vcc
	v_cmp_lt_i32_e32 vcc, 15, v112
	s_nop 1
	v_cndmask_b32_e32 v88, v245, v88, vcc
	v_cmp_lt_i32_e32 vcc, -1, v113
	v_subrev_u32_e32 v113, 18, v112
	s_nop 0
	v_cndmask_b32_e32 v89, v245, v89, vcc
	v_cmp_lt_i32_e32 vcc, -1, v113
	v_subrev_u32_e32 v113, 19, v112
	s_nop 0
	v_cndmask_b32_e32 v90, v245, v90, vcc
	v_cmp_lt_i32_e32 vcc, -1, v113
	v_subrev_u32_e32 v113, 24, v112
	s_nop 0
	v_cndmask_b32_e32 v91, v245, v91, vcc
	v_cmp_lt_i32_e32 vcc, -1, v113
	v_subrev_u32_e32 v113, 25, v112
	s_nop 0
	v_cndmask_b32_e32 v92, v245, v92, vcc
	v_cmp_lt_i32_e32 vcc, -1, v113
	v_subrev_u32_e32 v113, 26, v112
	v_subrev_u32_e32 v112, 27, v112
	v_cndmask_b32_e32 v93, v245, v93, vcc
	v_cmp_lt_i32_e32 vcc, -1, v113
	s_nop 1
	v_cndmask_b32_e32 v94, v245, v94, vcc
	v_cmp_lt_i32_e32 vcc, -1, v112
	s_nop 1
	v_cndmask_b32_e32 v95, v245, v95, vcc
.LBB0_569:
	v_add_f32_e32 v96, 0, v96
	v_add_f32_e32 v97, 0, v97
	v_add_f32_e32 v96, v98, v96
	v_add_f32_e32 v97, v99, v97
	v_add_f32_e32 v96, v100, v96
	v_add_f32_e32 v97, v101, v97
	v_add_f32_e32 v96, v102, v96
	v_add_f32_e32 v97, v103, v97
	v_add_f32_e32 v96, v104, v96
	v_add_f32_e32 v97, v105, v97
	v_add_f32_e32 v96, v106, v96
	v_add_f32_e32 v97, v107, v97
	v_add_f32_e32 v96, v108, v96
	v_add_f32_e32 v97, v109, v97
	v_add_f32_e32 v96, v110, v96
	v_add_f32_e32 v97, v111, v97
	v_exp_f32_e32 v80, v80
	v_exp_f32_e32 v81, v81
	v_add_f32_e32 v96, v96, v97
	v_exp_f32_e32 v82, v82
	v_exp_f32_e32 v83, v83
	v_cndmask_b32_e64 v96, 0, v96, s[20:21]
	v_exp_f32_e32 v84, v84
	v_exp_f32_e32 v85, v85
	v_add_f32_e32 v189, v189, v96
	v_and_b32_e32 v96, s90, v249
	v_exp_f32_e32 v86, v86
	v_exp_f32_e32 v87, v87
	v_cmp_ne_u32_e32 vcc, 0, v96
	v_exp_f32_e32 v88, v88
	v_exp_f32_e32 v89, v89
	v_pk_add_f32 v[96:97], v[80:81], 0 op_sel_hi:[1,0]
	v_exp_f32_e32 v90, v90
	v_exp_f32_e32 v91, v91
	v_pk_add_f32 v[96:97], v[82:83], v[96:97]
	v_exp_f32_e32 v92, v92
	v_exp_f32_e32 v93, v93
	v_pk_add_f32 v[96:97], v[84:85], v[96:97]
	v_exp_f32_e32 v94, v94
	v_exp_f32_e32 v95, v95
	v_pk_add_f32 v[96:97], v[86:87], v[96:97]
	v_cvt_pk_bf16_f32 v80, v80, v81
	v_pk_add_f32 v[96:97], v[88:89], v[96:97]
	v_cvt_pk_bf16_f32 v81, v82, v83
	v_pk_add_f32 v[96:97], v[90:91], v[96:97]
	v_cvt_pk_bf16_f32 v82, v84, v85
	v_pk_add_f32 v[96:97], v[92:93], v[96:97]
	v_cvt_pk_bf16_f32 v83, v86, v87
	v_pk_add_f32 v[96:97], v[94:95], v[96:97]
	v_cvt_pk_bf16_f32 v84, v88, v89
	v_cvt_pk_bf16_f32 v85, v90, v91
	v_cvt_pk_bf16_f32 v86, v92, v93
	v_cvt_pk_bf16_f32 v87, v94, v95
	s_or_b64 vcc, s[16:17], vcc
	v_cndmask_b32_e32 v80, 0, v80, vcc
	v_cndmask_b32_e32 v81, 0, v81, vcc
	v_cndmask_b32_e32 v82, 0, v82, vcc
	v_cndmask_b32_e32 v83, 0, v83, vcc
	v_cndmask_b32_e32 v84, 0, v84, vcc
	v_cndmask_b32_e32 v85, 0, v85, vcc
	v_mfma_f32_32x32x16_bf16 v[16:31], v[152:155], v[80:83], v[16:31]
	v_cndmask_b32_e32 v86, 0, v86, vcc
	v_cndmask_b32_e32 v87, 0, v87, vcc
	v_add_f32_e32 v96, v96, v97
	v_cndmask_b32_e32 v96, 0, v96, vcc
	v_add_f32_e32 v183, v183, v96
	s_andn2_b64 vcc, exec, s[82:83]
	v_mfma_f32_32x32x16_bf16 v[0:15], v[168:171], v[80:83], v[0:15]
	v_mfma_f32_32x32x16_bf16 v[16:31], v[160:163], v[84:87], v[16:31]
	v_mfma_f32_32x32x16_bf16 v[0:15], v[176:179], v[84:87], v[0:15]
	global_load_dwordx4 v[152:155], v207, s[80:81]
	global_load_dwordx4 v[160:163], v207, s[80:81] offset:1024
	global_load_dwordx4 v[168:171], v207, s[80:81] offset:2048
	global_load_dwordx4 v[176:179], v207, s[80:81] offset:3072
	s_cbranch_vccz .LBB0_571
	s_mov_b32 s21, s88
	s_mov_b32 s20, s89
	s_branch .LBB0_563

; #define LAS __attribute__((address_space(3)))
; #define MFMA32(a, b, c) __builtin_amdgcn_mfma_f32_32x32x16_bf16((a), (b), (c), 0, 0, 0)
; DI void core1g(ASt& st, const bf16x8 (&qf)[4], LAS unsigned char* buf, bool ok, float m0, int lane) {
;     const int r = lane & 31, h = lane >> 5;
;     f32x16 s;
;     {
;         const f32x16 zero = {0.f, 0.f, 0.f, 0.f, 0.f, 0.f, 0.f, 0.f, 0.f, 0.f, 0.f, 0.f, 0.f, 0.f, 0.f, 0.f};
;         const bf16x8 kf = lds_frag(buf + r * TROW + h * 16); s = MFMA32(kf, qf[0], zero);
;     }
; #pragma unroll
;     for (int ks = 1; ks < 4; ++ks) { const bf16x8 kf = lds_frag(buf + r * TROW + (2 * ks + h) * 16); s = MFMA32(kf, qf[ks], s); }
;     LAS unsigned char* vb = buf + 32 * TROW + (4 * h + ((lane & 15) >> 2)) * TROW + 32 * ((lane >> 4) & 1) + 8 * (lane & 3);
;     softmax_p<true>(st, s, 0, 0, 0, ok, false, m0);
;     bf16x8 p[2]; pack_p(p, s, ok);
; #pragma unroll
;     for (int s2 = 0; s2 < 2; ++s2) {
;         const bf16x8 v0 = load_vfrag1(vb, 0, s2), v1 = load_vfrag1(vb, 1, s2);
;         st.o0 = MFMA32(v0, p[s2], st.o0); st.o1 = MFMA32(v1, p[s2], st.o1);
;     }
; }
; DI void attn_b_item(unsigned char* ws, LAS unsigned char* buf, LAS unsigned char* qbuf, LAS unsigned* tbl, LAS float* km  , int bh, int qblk, int w4, int lane) {
;     ...
;             for (int T = 0; T < 8; ++T) {
;                 tile_lds_write(buf, tr, lane);
;                 if (T < 7) tile_gload(tr, K, V, n * 256 + 32 * (T + 1), 1, lane);
;                 else if (nn >= 0) tile_gload(tr, K, V, nn * 256, 1, lane);
;                 core1g(g, gq, buf, okg, m0, lane);
;             }
.Lg_off_done:
	s_add_i32 s88, s88, 0x1000
	s_cmpk_eq_u32 s88, 0x8000
	s_waitcnt vmcnt(7)
	v_mfma_f32_32x32x16_bf16 v[96:111], v[116:119], v[148:151], 0
	s_waitcnt vmcnt(6)
	v_mfma_f32_32x32x16_bf16 v[96:111], v[120:123], v[152:155], v[96:111]
	s_waitcnt vmcnt(5)
	v_mfma_f32_32x32x16_bf16 v[96:111], v[124:127], v[156:159], v[96:111]
	v_add_u32_e32 v193, s90, v191
	s_waitcnt vmcnt(4)
	v_mfma_f32_32x32x16_bf16 v[96:111], v[128:131], v[160:163], v[96:111]
	global_load_dwordx4 v[116:119], v193, s[78:79]
	global_load_dwordx4 v[120:123], v193, s[78:79] offset:1024
	global_load_dwordx4 v[124:127], v193, s[78:79] offset:2048
	global_load_dwordx4 v[128:131], v193, s[78:79] offset:3072
	s_nop 7
	v_sub_f32_e32 v96, v96, v247
	v_sub_f32_e32 v97, v97, v247
	v_sub_f32_e32 v98, v98, v247
	v_sub_f32_e32 v99, v99, v247
	v_exp_f32_e32 v96, v96
	v_exp_f32_e32 v97, v97
	v_sub_f32_e32 v100, v100, v247
	v_sub_f32_e32 v101, v101, v247
	v_exp_f32_e32 v98, v98
	v_exp_f32_e32 v99, v99
	v_sub_f32_e32 v102, v102, v247
	v_sub_f32_e32 v103, v103, v247
	v_exp_f32_e32 v100, v100
	v_exp_f32_e32 v101, v101
	v_sub_f32_e32 v104, v104, v247
	v_sub_f32_e32 v105, v105, v247
	v_sub_f32_e32 v108, v108, v247
	v_sub_f32_e32 v109, v109, v247
	v_exp_f32_e32 v102, v102
	v_exp_f32_e32 v103, v103
	v_exp_f32_e32 v104, v104
	v_exp_f32_e32 v105, v105
	v_exp_f32_e32 v168, v108
	v_exp_f32_e32 v169, v109
	v_pk_add_f32 v[108:109], v[96:97], 0 op_sel_hi:[1,0]
	v_cvt_pk_bf16_f32 v96, v96, v97
	v_cvt_pk_bf16_f32 v97, v98, v99
	v_pk_add_f32 v[98:99], v[98:99], v[108:109]
	v_sub_f32_e32 v106, v106, v247
	v_pk_add_f32 v[98:99], v[100:101], v[98:99]
	v_sub_f32_e32 v107, v107, v247
	v_pk_add_f32 v[98:99], v[102:103], v[98:99]
	v_sub_f32_e32 v110, v110, v247
	v_pk_add_f32 v[108:109], v[104:105], v[98:99]
	v_cvt_pk_bf16_f32 v98, v100, v101
	v_cvt_pk_bf16_f32 v99, v102, v103
	v_sub_f32_e32 v111, v111, v247
	v_exp_f32_e32 v106, v106
	v_exp_f32_e32 v107, v107
	v_exp_f32_e32 v170, v110
	v_exp_f32_e32 v171, v111
	v_cndmask_b32_e64 v96, 0, v96, s[20:21]
	v_cndmask_b32_e64 v97, 0, v97, s[20:21]
	v_cndmask_b32_e64 v98, 0, v98, s[20:21]
	v_cndmask_b32_e64 v99, 0, v99, s[20:21]
	v_pk_add_f32 v[108:109], v[106:107], v[108:109]
	v_cvt_pk_bf16_f32 v104, v104, v105
	s_waitcnt vmcnt(7)
	v_mfma_f32_32x32x16_bf16 v[64:79], v[132:135], v[96:99], v[64:79]
	v_cvt_pk_bf16_f32 v105, v106, v107
	v_add_f32_e64 v164, v168, v108
	v_add_f32_e64 v165, v169, v109
	v_cndmask_b32_e64 v104, 0, v104, s[20:21]
	v_cndmask_b32_e64 v105, 0, v105, s[20:21]
	s_waitcnt vmcnt(5)
	v_mfma_f32_32x32x16_bf16 v[80:95], v[140:143], v[96:99], v[80:95]
	v_cvt_pk_bf16_f32 v96, v168, v169
	v_cndmask_b32_e64 v106, 0, v96, s[20:21]
	v_cvt_pk_bf16_f32 v96, v170, v171
	v_cndmask_b32_e64 v107, 0, v96, s[20:21]
	v_pk_add_f32 v[100:101], v[170:171], v[164:165]
	s_nop 0
	v_mfma_f32_32x32x16_bf16 v[64:79], v[136:139], v[104:107], v[64:79]
	v_add_f32_e32 v100, v100, v101
	v_cndmask_b32_e64 v100, 0, v100, s[20:21]
	v_add_f32_e32 v112, v112, v100
	s_waitcnt vmcnt(4)
	v_mfma_f32_32x32x16_bf16 v[80:95], v[144:147], v[104:107], v[80:95]
	global_load_dwordx4 v[132:135], v193, s[80:81]
	global_load_dwordx4 v[136:139], v193, s[80:81] offset:1024
	global_load_dwordx4 v[140:143], v193, s[80:81] offset:2048
	global_load_dwordx4 v[144:147], v193, s[80:81] offset:3072
	s_cbranch_scc1 .LBB0_589
	s_branch .LBB0_581
